# XCD-local seams: P1-P2 and P9-P10 drop the L2 writeback (data is read back through the same L2); P7-P8 and P8-P9 become XCD-local without writeback (producer and consumer row panels share an XCD)
# speedup vs baseline: 1.0114x; 1.0102x over previous
.LBB0_347:
	s_andn2_saveexec_b64 s[14:15], s[14:15]
	s_cbranch_execz .LBB0_403
	s_waitcnt lgkmcnt(0)
	v_readlane_b32 s14, v250, 4
	s_waitcnt vmcnt(0)
	v_readlane_b32 s15, v250, 5
	s_andn2_b64 vcc, exec, s[14:15]
	s_cbranch_vccnz .LBB0_400
	s_mov_b64 s[24:25], exec
	v_mbcnt_lo_u32_b32 v1, s24, 0
	v_mbcnt_hi_u32_b32 v1, s25, v1
	v_cmp_eq_u32_e32 vcc, 0, v1
	s_and_saveexec_b64 s[14:15], vcc
	s_cbranch_execz .LBB0_351
	s_bcnt1_i32_b64 s17, s[24:25]
	v_mov_b32_e32 v2, s17
	global_atomic_add v2, v224, v2, s[10:11] offset:1024 sc0

.LBB0_1776:
	s_andn2_saveexec_b64 s[14:15], s[14:15]
	s_cbranch_execz .LBB0_1799
	s_mov_b64 s[14:15], exec
	s_waitcnt lgkmcnt(0)
	s_waitcnt vmcnt(0)
	s_branch .Lseam8_local
	v_mbcnt_lo_u32_b32 v1, s14, 0
	v_mbcnt_hi_u32_b32 v1, s15, v1
	v_cmp_eq_u32_e32 vcc, 0, v1
	s_and_saveexec_b64 s[24:25], vcc
	s_cbranch_execz .LBB0_1779
	s_bcnt1_i32_b64 s14, s[14:15]
	v_mov_b32_e32 v2, s14
	global_atomic_add v2, v224, v2, s[10:11] offset:1024 sc0

.LBB0_1878:
	s_andn2_saveexec_b64 s[14:15], s[14:15]
	s_cbranch_execz .LBB0_1901
	s_mov_b64 s[14:15], exec
	s_waitcnt lgkmcnt(0)
	s_waitcnt vmcnt(0)
	s_branch .Lseam9_local
	v_mbcnt_lo_u32_b32 v0, s14, 0
	v_mbcnt_hi_u32_b32 v0, s15, v0
	v_cmp_eq_u32_e32 vcc, 0, v0
	s_and_saveexec_b64 s[24:25], vcc
	s_cbranch_execz .LBB0_1881
	s_bcnt1_i32_b64 s14, s[14:15]
	v_mov_b32_e32 v2, s14
	global_atomic_add v2, v224, v2, s[10:11] offset:1024 sc0
